# SSD X-conv straight path when all taps in range (tap-batched loads, 4 waits instead of 16)
# speedup vs baseline: 1.0080x; 1.0019x over previous
.Lssdb_tail:
	s_waitcnt vmcnt(2)
	v_mul_f32_e32 v32, 0xbfb8aa3b, v20
	v_exp_f32_e32 v32, v32
	s_lshl_b32 s33, s42, 6
	v_add_f32_e32 v32, 1.0, v32
	v_rcp_f32_e32 v32, v32
	s_nop 0
	v_mul_f32_e32 v20, v20, v32
	v_mul_f32_e32 v32, 0xbfb8aa3b, v21
	v_exp_f32_e32 v32, v32
	s_nop 0
	v_add_f32_e32 v32, 1.0, v32
	v_rcp_f32_e32 v32, v32
	s_nop 0
	v_mul_f32_e32 v21, v21, v32
	v_mul_f32_e32 v32, 0xbfb8aa3b, v22
	v_exp_f32_e32 v32, v32
	s_nop 0
	v_add_f32_e32 v32, 1.0, v32
	v_rcp_f32_e32 v32, v32
	s_nop 0
	v_mul_f32_e32 v22, v22, v32
	v_mul_f32_e32 v32, 0xbfb8aa3b, v23
	v_exp_f32_e32 v32, v32
	s_nop 0
	v_add_f32_e32 v32, 1.0, v32
	v_rcp_f32_e32 v32, v32
	s_nop 0
	v_mul_f32_e32 v23, v23, v32
	v_mul_f32_e32 v32, 0xbfb8aa3b, v16
	v_exp_f32_e32 v32, v32
	s_nop 0
	v_add_f32_e32 v32, 1.0, v32
	v_rcp_f32_e32 v32, v32
	s_nop 0
	v_mul_f32_e32 v16, v16, v32
	v_mul_f32_e32 v32, 0xbfb8aa3b, v17
	v_exp_f32_e32 v32, v32
	s_nop 0
	v_add_f32_e32 v32, 1.0, v32
	v_rcp_f32_e32 v32, v32
	s_nop 0
	v_mul_f32_e32 v17, v17, v32
	v_mul_f32_e32 v32, 0xbfb8aa3b, v18
	v_exp_f32_e32 v32, v32
	s_nop 0
	v_add_f32_e32 v32, 1.0, v32
	v_rcp_f32_e32 v32, v32
	s_nop 0
	v_mul_f32_e32 v18, v18, v32
	v_mul_f32_e32 v32, 0xbfb8aa3b, v19
	v_exp_f32_e32 v32, v32
	s_nop 0
	v_add_f32_e32 v32, 1.0, v32
	v_rcp_f32_e32 v32, v32
	s_nop 0
	v_mul_f32_e32 v19, v19, v32
	v_mul_f32_e32 v32, 0xbfb8aa3b, v12
	v_exp_f32_e32 v32, v32
	s_nop 0
	v_add_f32_e32 v32, 1.0, v32
	v_rcp_f32_e32 v32, v32
	s_nop 0
	v_mul_f32_e32 v12, v12, v32
	v_mul_f32_e32 v32, 0xbfb8aa3b, v13
	v_exp_f32_e32 v32, v32
	s_nop 0
	v_add_f32_e32 v32, 1.0, v32
	v_rcp_f32_e32 v32, v32
	s_nop 0
	v_mul_f32_e32 v13, v13, v32
	v_mul_f32_e32 v32, 0xbfb8aa3b, v14
	v_exp_f32_e32 v32, v32
	s_nop 0
	v_add_f32_e32 v32, 1.0, v32
	v_rcp_f32_e32 v32, v32
	s_nop 0
	v_mul_f32_e32 v14, v14, v32
	v_mul_f32_e32 v32, 0xbfb8aa3b, v15
	v_exp_f32_e32 v32, v32
	s_nop 0
	v_add_f32_e32 v32, 1.0, v32
	v_rcp_f32_e32 v32, v32
	s_nop 0
	v_mul_f32_e32 v15, v15, v32
	v_mul_f32_e32 v32, 0xbfb8aa3b, v8
	v_exp_f32_e32 v32, v32
	s_nop 0
	v_add_f32_e32 v32, 1.0, v32
	v_rcp_f32_e32 v32, v32
	s_nop 0
	v_mul_f32_e32 v8, v8, v32
	v_mul_f32_e32 v32, 0xbfb8aa3b, v9
	v_exp_f32_e32 v32, v32
	s_nop 0
	v_add_f32_e32 v32, 1.0, v32
	v_rcp_f32_e32 v32, v32
	s_nop 0
	v_mul_f32_e32 v9, v9, v32
	v_mul_f32_e32 v32, 0xbfb8aa3b, v10
	v_exp_f32_e32 v32, v32
	s_nop 0
	v_add_f32_e32 v32, 1.0, v32
	v_rcp_f32_e32 v32, v32
	s_nop 0
	v_mul_f32_e32 v10, v10, v32
	v_mul_f32_e32 v32, 0xbfb8aa3b, v11
	v_exp_f32_e32 v32, v32
	s_nop 0
	v_add_f32_e32 v32, 1.0, v32
	v_rcp_f32_e32 v32, v32
	s_nop 0
	v_mul_f32_e32 v11, v11, v32
	v_mul_f32_e32 v32, 0xbfb8aa3b, v4
	v_exp_f32_e32 v32, v32
	s_nop 0
	v_add_f32_e32 v32, 1.0, v32
	v_rcp_f32_e32 v32, v32
	s_nop 0
	v_mul_f32_e32 v4, v4, v32
	v_mul_f32_e32 v32, 0xbfb8aa3b, v5
	v_exp_f32_e32 v32, v32
	s_nop 0
	v_add_f32_e32 v32, 1.0, v32
	v_rcp_f32_e32 v32, v32
	s_nop 0
	v_mul_f32_e32 v5, v5, v32
	v_mul_f32_e32 v32, 0xbfb8aa3b, v6
	v_exp_f32_e32 v32, v32
	s_nop 0
	v_add_f32_e32 v32, 1.0, v32
	v_rcp_f32_e32 v32, v32
	s_nop 0
	v_mul_f32_e32 v6, v6, v32
	v_mul_f32_e32 v32, 0xbfb8aa3b, v7
	v_exp_f32_e32 v32, v32
	s_nop 0
	v_add_f32_e32 v32, 1.0, v32
	v_rcp_f32_e32 v32, v32
	s_nop 0
	v_mul_f32_e32 v7, v7, v32
	v_mul_f32_e32 v32, 0xbfb8aa3b, v0
	v_exp_f32_e32 v32, v32
	s_nop 0
	v_add_f32_e32 v32, 1.0, v32
	v_rcp_f32_e32 v32, v32
	s_nop 0
	v_mul_f32_e32 v32, v0, v32
	v_mul_f32_e32 v0, 0xbfb8aa3b, v1
	v_exp_f32_e32 v0, v0
	s_nop 0
	v_add_f32_e32 v0, 1.0, v0
	v_rcp_f32_e32 v0, v0
	s_nop 0
	v_mul_f32_e32 v33, v1, v0
	v_mul_f32_e32 v0, 0xbfb8aa3b, v2
	v_exp_f32_e32 v0, v0
	v_lshlrev_b32_e32 v1, 6, v39
	v_add_f32_e32 v0, 1.0, v0
	v_rcp_f32_e32 v0, v0
	s_nop 0
	v_mul_f32_e32 v34, v2, v0
	v_mul_f32_e32 v0, 0xbfb8aa3b, v3
	v_exp_f32_e32 v0, v0
	v_cvt_pk_bf16_f32 v2, v32, v33
	v_add_f32_e32 v0, 1.0, v0
	v_rcp_f32_e32 v0, v0
	s_nop 0
	v_mul_f32_e32 v3, v3, v0
	s_waitcnt vmcnt(0)
	v_mul_f32_e32 v0, 0xbfb8aa3b, v28
	v_exp_f32_e32 v0, v0
	v_cvt_pk_bf16_f32 v3, v34, v3
	v_add_f32_e32 v0, 1.0, v0
	v_rcp_f32_e32 v0, v0
	s_nop 0
	v_mul_f32_e32 v28, v28, v0
	v_mul_f32_e32 v0, 0xbfb8aa3b, v29
	v_exp_f32_e32 v0, v0
	s_nop 0
	v_add_f32_e32 v0, 1.0, v0
	v_rcp_f32_e32 v0, v0
	s_nop 0
	v_mul_f32_e32 v29, v29, v0
	v_mul_f32_e32 v0, 0xbfb8aa3b, v30
	v_exp_f32_e32 v0, v0
	s_nop 0
	v_add_f32_e32 v0, 1.0, v0
	v_rcp_f32_e32 v0, v0
	s_nop 0
	v_mul_f32_e32 v30, v30, v0
	v_mul_f32_e32 v0, 0xbfb8aa3b, v31
	v_exp_f32_e32 v0, v0
	s_nop 0
	v_add_f32_e32 v0, 1.0, v0
	v_rcp_f32_e32 v0, v0
	s_nop 0
	v_mul_f32_e32 v31, v31, v0
	v_mul_f32_e32 v0, 0xbfb8aa3b, v24
	v_exp_f32_e32 v0, v0
	s_nop 0
	v_add_f32_e32 v0, 1.0, v0
	v_rcp_f32_e32 v0, v0
	s_nop 0
	v_mul_f32_e32 v24, v24, v0
	v_mul_f32_e32 v0, 0xbfb8aa3b, v25
	v_exp_f32_e32 v0, v0
	s_nop 0
	v_add_f32_e32 v0, 1.0, v0
	v_rcp_f32_e32 v0, v0
	s_nop 0
	v_mul_f32_e32 v25, v25, v0
	v_mul_f32_e32 v0, 0xbfb8aa3b, v26
	v_exp_f32_e32 v0, v0
	s_nop 0
	v_add_f32_e32 v0, 1.0, v0
	v_rcp_f32_e32 v0, v0
	s_nop 0
	v_mul_f32_e32 v26, v26, v0
	v_mul_f32_e32 v0, 0xbfb8aa3b, v27
	v_exp_f32_e32 v0, v0
	s_nop 0
	v_add_f32_e32 v0, 1.0, v0
	v_rcp_f32_e32 v0, v0
	s_nop 0
	v_mul_f32_e32 v27, v27, v0
	v_lshl_add_u32 v0, v45, 13, s89
	v_add_u32_e32 v36, v0, v1
	v_cvt_pk_bf16_f32 v0, v4, v5
	v_cvt_pk_bf16_f32 v1, v6, v7
	ds_write_b128 v36, v[0:3]
	v_cvt_pk_bf16_f32 v0, v12, v13
	v_cvt_pk_bf16_f32 v1, v14, v15
	v_cvt_pk_bf16_f32 v2, v8, v9
	v_cvt_pk_bf16_f32 v3, v10, v11
	ds_write_b128 v36, v[0:3] offset:16
	v_cvt_pk_bf16_f32 v0, v20, v21
	v_cvt_pk_bf16_f32 v1, v22, v23
	v_cvt_pk_bf16_f32 v2, v16, v17
	v_cvt_pk_bf16_f32 v3, v18, v19
	ds_write_b128 v36, v[0:3] offset:32
	v_cvt_pk_bf16_f32 v0, v28, v29
	v_cvt_pk_bf16_f32 v1, v30, v31
	v_cvt_pk_bf16_f32 v2, v24, v25
	v_cvt_pk_bf16_f32 v3, v26, v27
	ds_write_b128 v36, v[0:3] offset:48
	v_or_b32_e32 v0, s33, v44
	v_lshlrev_b32_e32 v168, 2, v0
	v_lshlrev_b32_e32 v0, 1, v0
	v_mov_b32_e32 v1, v169
	v_lshl_add_u64 v[34:35], s[30:31], 0, v[0:1]
	global_load_dwordx4 v[0:3], v168, s[74:75] offset:16
	global_load_dwordx4 v[4:7], v168, s[74:75]
	v_lshl_add_u64 v[32:33], s[14:15], 0, v[168:169]
	s_cmp_eq_u64 s[6:7], -1
	s_cbranch_scc0 .Lssdx_slow
	global_load_dwordx4 v[12:15], v168, s[74:75] offset:32
	global_load_dwordx4 v[8:11], v168, s[74:75] offset:48
	global_load_dwordx4 v[20:23], v168, s[74:75] offset:64
	global_load_dwordx4 v[16:19], v168, s[74:75] offset:80
	global_load_dwordx4 v[28:31], v168, s[74:75] offset:96
	global_load_dwordx4 v[24:27], v168, s[74:75] offset:112
	v_mad_i64_i32 v[48:49], s[0:1], v41, s93, v[34:35]
	v_mad_i64_i32 v[50:51], s[0:1], v42, s93, v[34:35]
	v_mad_i64_i32 v[52:53], s[0:1], v43, s93, v[34:35]
	v_mad_i64_i32 v[54:55], s[0:1], v40, s93, v[34:35]
	s_mov_b64 s[0:1], 0x1000
	v_lshl_add_u64 v[44:45], v[32:33], 0, s[0:1]
	global_load_dwordx4 v[92:95], v[48:49], off offset:1536
	global_load_dwordx4 v[96:99], v[48:49], off offset:1552
	global_load_dwordx4 v[100:103], v[48:49], off offset:1568
	global_load_dwordx4 v[104:107], v[48:49], off offset:1584
	global_load_dwordx4 v[108:111], v[32:33], off offset:0
	global_load_dwordx4 v[112:115], v[32:33], off offset:16
	global_load_dwordx4 v[116:119], v[32:33], off offset:32
	global_load_dwordx4 v[120:123], v[32:33], off offset:48
	global_load_dwordx4 v[124:127], v[32:33], off offset:64
	global_load_dwordx4 v[128:131], v[32:33], off offset:80
	global_load_dwordx4 v[132:135], v[32:33], off offset:96
	global_load_dwordx4 v[136:139], v[32:33], off offset:112
	s_waitcnt vmcnt(0)
	v_lshlrev_b32_e32 v140, 16, v92
	v_and_b32_e32 v141, 0xffff0000, v92
	v_pk_fma_f32 v[4:5], v[108:109], v[140:141], v[4:5]
	v_lshlrev_b32_e32 v140, 16, v93
	v_and_b32_e32 v141, 0xffff0000, v93
	v_pk_fma_f32 v[6:7], v[110:111], v[140:141], v[6:7]
	v_lshlrev_b32_e32 v140, 16, v94
	v_and_b32_e32 v141, 0xffff0000, v94
	v_pk_fma_f32 v[0:1], v[112:113], v[140:141], v[0:1]
	v_lshlrev_b32_e32 v140, 16, v95
	v_and_b32_e32 v141, 0xffff0000, v95
	v_pk_fma_f32 v[2:3], v[114:115], v[140:141], v[2:3]
	v_lshlrev_b32_e32 v140, 16, v96
	v_and_b32_e32 v141, 0xffff0000, v96
	v_pk_fma_f32 v[12:13], v[116:117], v[140:141], v[12:13]
	v_lshlrev_b32_e32 v140, 16, v97
	v_and_b32_e32 v141, 0xffff0000, v97
	v_pk_fma_f32 v[14:15], v[118:119], v[140:141], v[14:15]
	v_lshlrev_b32_e32 v140, 16, v98
	v_and_b32_e32 v141, 0xffff0000, v98
	v_pk_fma_f32 v[8:9], v[120:121], v[140:141], v[8:9]
	v_lshlrev_b32_e32 v140, 16, v99
	v_and_b32_e32 v141, 0xffff0000, v99
	v_pk_fma_f32 v[10:11], v[122:123], v[140:141], v[10:11]
	v_lshlrev_b32_e32 v140, 16, v100
	v_and_b32_e32 v141, 0xffff0000, v100
	v_pk_fma_f32 v[20:21], v[124:125], v[140:141], v[20:21]
	v_lshlrev_b32_e32 v140, 16, v101
	v_and_b32_e32 v141, 0xffff0000, v101
	v_pk_fma_f32 v[22:23], v[126:127], v[140:141], v[22:23]
	v_lshlrev_b32_e32 v140, 16, v102
	v_and_b32_e32 v141, 0xffff0000, v102
	v_pk_fma_f32 v[16:17], v[128:129], v[140:141], v[16:17]
	v_lshlrev_b32_e32 v140, 16, v103
	v_and_b32_e32 v141, 0xffff0000, v103
	v_pk_fma_f32 v[18:19], v[130:131], v[140:141], v[18:19]
	v_lshlrev_b32_e32 v140, 16, v104
	v_and_b32_e32 v141, 0xffff0000, v104
	v_pk_fma_f32 v[28:29], v[132:133], v[140:141], v[28:29]
	v_lshlrev_b32_e32 v140, 16, v105
	v_and_b32_e32 v141, 0xffff0000, v105
	v_pk_fma_f32 v[30:31], v[134:135], v[140:141], v[30:31]
	v_lshlrev_b32_e32 v140, 16, v106
	v_and_b32_e32 v141, 0xffff0000, v106
	v_pk_fma_f32 v[24:25], v[136:137], v[140:141], v[24:25]
	v_lshlrev_b32_e32 v140, 16, v107
	v_and_b32_e32 v141, 0xffff0000, v107
	v_pk_fma_f32 v[26:27], v[138:139], v[140:141], v[26:27]
	global_load_dwordx4 v[92:95], v[50:51], off offset:1536
	global_load_dwordx4 v[96:99], v[50:51], off offset:1552
	global_load_dwordx4 v[100:103], v[50:51], off offset:1568
	global_load_dwordx4 v[104:107], v[50:51], off offset:1584
	global_load_dwordx4 v[108:111], v[32:33], off offset:2048
	global_load_dwordx4 v[112:115], v[32:33], off offset:2064
	global_load_dwordx4 v[116:119], v[32:33], off offset:2080
	global_load_dwordx4 v[120:123], v[32:33], off offset:2096
	global_load_dwordx4 v[124:127], v[32:33], off offset:2112
	global_load_dwordx4 v[128:131], v[32:33], off offset:2128
	global_load_dwordx4 v[132:135], v[32:33], off offset:2144
	global_load_dwordx4 v[136:139], v[32:33], off offset:2160
	s_waitcnt vmcnt(0)
	v_lshlrev_b32_e32 v140, 16, v92
	v_and_b32_e32 v141, 0xffff0000, v92
	v_pk_fma_f32 v[4:5], v[108:109], v[140:141], v[4:5]
	v_lshlrev_b32_e32 v140, 16, v93
	v_and_b32_e32 v141, 0xffff0000, v93
	v_pk_fma_f32 v[6:7], v[110:111], v[140:141], v[6:7]
	v_lshlrev_b32_e32 v140, 16, v94
	v_and_b32_e32 v141, 0xffff0000, v94
	v_pk_fma_f32 v[0:1], v[112:113], v[140:141], v[0:1]
	v_lshlrev_b32_e32 v140, 16, v95
	v_and_b32_e32 v141, 0xffff0000, v95
	v_pk_fma_f32 v[2:3], v[114:115], v[140:141], v[2:3]
	v_lshlrev_b32_e32 v140, 16, v96
	v_and_b32_e32 v141, 0xffff0000, v96
	v_pk_fma_f32 v[12:13], v[116:117], v[140:141], v[12:13]
	v_lshlrev_b32_e32 v140, 16, v97
	v_and_b32_e32 v141, 0xffff0000, v97
	v_pk_fma_f32 v[14:15], v[118:119], v[140:141], v[14:15]
	v_lshlrev_b32_e32 v140, 16, v98
	v_and_b32_e32 v141, 0xffff0000, v98
	v_pk_fma_f32 v[8:9], v[120:121], v[140:141], v[8:9]
	v_lshlrev_b32_e32 v140, 16, v99
	v_and_b32_e32 v141, 0xffff0000, v99
	v_pk_fma_f32 v[10:11], v[122:123], v[140:141], v[10:11]
	v_lshlrev_b32_e32 v140, 16, v100
	v_and_b32_e32 v141, 0xffff0000, v100
	v_pk_fma_f32 v[20:21], v[124:125], v[140:141], v[20:21]
	v_lshlrev_b32_e32 v140, 16, v101
	v_and_b32_e32 v141, 0xffff0000, v101
	v_pk_fma_f32 v[22:23], v[126:127], v[140:141], v[22:23]
	v_lshlrev_b32_e32 v140, 16, v102
	v_and_b32_e32 v141, 0xffff0000, v102
	v_pk_fma_f32 v[16:17], v[128:129], v[140:141], v[16:17]
	v_lshlrev_b32_e32 v140, 16, v103
	v_and_b32_e32 v141, 0xffff0000, v103
	v_pk_fma_f32 v[18:19], v[130:131], v[140:141], v[18:19]
	v_lshlrev_b32_e32 v140, 16, v104
	v_and_b32_e32 v141, 0xffff0000, v104
	v_pk_fma_f32 v[28:29], v[132:133], v[140:141], v[28:29]
	v_lshlrev_b32_e32 v140, 16, v105
	v_and_b32_e32 v141, 0xffff0000, v105
	v_pk_fma_f32 v[30:31], v[134:135], v[140:141], v[30:31]
	v_lshlrev_b32_e32 v140, 16, v106
	v_and_b32_e32 v141, 0xffff0000, v106
	v_pk_fma_f32 v[24:25], v[136:137], v[140:141], v[24:25]
	v_lshlrev_b32_e32 v140, 16, v107
	v_and_b32_e32 v141, 0xffff0000, v107
	v_pk_fma_f32 v[26:27], v[138:139], v[140:141], v[26:27]
	global_load_dwordx4 v[92:95], v[52:53], off offset:1536
	global_load_dwordx4 v[96:99], v[52:53], off offset:1552
	global_load_dwordx4 v[100:103], v[52:53], off offset:1568
	global_load_dwordx4 v[104:107], v[52:53], off offset:1584
	global_load_dwordx4 v[108:111], v[44:45], off offset:0
	global_load_dwordx4 v[112:115], v[44:45], off offset:16
	global_load_dwordx4 v[116:119], v[44:45], off offset:32
	global_load_dwordx4 v[120:123], v[44:45], off offset:48
	global_load_dwordx4 v[124:127], v[44:45], off offset:64
	global_load_dwordx4 v[128:131], v[44:45], off offset:80
	global_load_dwordx4 v[132:135], v[44:45], off offset:96
	global_load_dwordx4 v[136:139], v[44:45], off offset:112
	s_waitcnt vmcnt(0)
	v_lshlrev_b32_e32 v140, 16, v92
	v_and_b32_e32 v141, 0xffff0000, v92
	v_pk_fma_f32 v[4:5], v[108:109], v[140:141], v[4:5]
	v_lshlrev_b32_e32 v140, 16, v93
	v_and_b32_e32 v141, 0xffff0000, v93
	v_pk_fma_f32 v[6:7], v[110:111], v[140:141], v[6:7]
	v_lshlrev_b32_e32 v140, 16, v94
	v_and_b32_e32 v141, 0xffff0000, v94
	v_pk_fma_f32 v[0:1], v[112:113], v[140:141], v[0:1]
	v_lshlrev_b32_e32 v140, 16, v95
	v_and_b32_e32 v141, 0xffff0000, v95
	v_pk_fma_f32 v[2:3], v[114:115], v[140:141], v[2:3]
	v_lshlrev_b32_e32 v140, 16, v96
	v_and_b32_e32 v141, 0xffff0000, v96
	v_pk_fma_f32 v[12:13], v[116:117], v[140:141], v[12:13]
	v_lshlrev_b32_e32 v140, 16, v97
	v_and_b32_e32 v141, 0xffff0000, v97
	v_pk_fma_f32 v[14:15], v[118:119], v[140:141], v[14:15]
	v_lshlrev_b32_e32 v140, 16, v98
	v_and_b32_e32 v141, 0xffff0000, v98
	v_pk_fma_f32 v[8:9], v[120:121], v[140:141], v[8:9]
	v_lshlrev_b32_e32 v140, 16, v99
	v_and_b32_e32 v141, 0xffff0000, v99
	v_pk_fma_f32 v[10:11], v[122:123], v[140:141], v[10:11]
	v_lshlrev_b32_e32 v140, 16, v100
	v_and_b32_e32 v141, 0xffff0000, v100
	v_pk_fma_f32 v[20:21], v[124:125], v[140:141], v[20:21]
	v_lshlrev_b32_e32 v140, 16, v101
	v_and_b32_e32 v141, 0xffff0000, v101
	v_pk_fma_f32 v[22:23], v[126:127], v[140:141], v[22:23]
	v_lshlrev_b32_e32 v140, 16, v102
	v_and_b32_e32 v141, 0xffff0000, v102
	v_pk_fma_f32 v[16:17], v[128:129], v[140:141], v[16:17]
	v_lshlrev_b32_e32 v140, 16, v103
	v_and_b32_e32 v141, 0xffff0000, v103
	v_pk_fma_f32 v[18:19], v[130:131], v[140:141], v[18:19]
	v_lshlrev_b32_e32 v140, 16, v104
	v_and_b32_e32 v141, 0xffff0000, v104
	v_pk_fma_f32 v[28:29], v[132:133], v[140:141], v[28:29]
	v_lshlrev_b32_e32 v140, 16, v105
	v_and_b32_e32 v141, 0xffff0000, v105
	v_pk_fma_f32 v[30:31], v[134:135], v[140:141], v[30:31]
	v_lshlrev_b32_e32 v140, 16, v106
	v_and_b32_e32 v141, 0xffff0000, v106
	v_pk_fma_f32 v[24:25], v[136:137], v[140:141], v[24:25]
	v_lshlrev_b32_e32 v140, 16, v107
	v_and_b32_e32 v141, 0xffff0000, v107
	v_pk_fma_f32 v[26:27], v[138:139], v[140:141], v[26:27]
	global_load_dwordx4 v[92:95], v[54:55], off offset:1536
	global_load_dwordx4 v[96:99], v[54:55], off offset:1552
	global_load_dwordx4 v[100:103], v[54:55], off offset:1568
	global_load_dwordx4 v[104:107], v[54:55], off offset:1584
	global_load_dwordx4 v[108:111], v[44:45], off offset:2048
	global_load_dwordx4 v[112:115], v[44:45], off offset:2064
	global_load_dwordx4 v[116:119], v[44:45], off offset:2080
	global_load_dwordx4 v[120:123], v[44:45], off offset:2096
	global_load_dwordx4 v[124:127], v[44:45], off offset:2112
	global_load_dwordx4 v[128:131], v[44:45], off offset:2128
	global_load_dwordx4 v[132:135], v[44:45], off offset:2144
	global_load_dwordx4 v[136:139], v[44:45], off offset:2160
	s_waitcnt vmcnt(0)
	v_lshlrev_b32_e32 v140, 16, v92
	v_and_b32_e32 v141, 0xffff0000, v92
	v_pk_fma_f32 v[4:5], v[108:109], v[140:141], v[4:5]
	v_lshlrev_b32_e32 v140, 16, v93
	v_and_b32_e32 v141, 0xffff0000, v93
	v_pk_fma_f32 v[6:7], v[110:111], v[140:141], v[6:7]
	v_lshlrev_b32_e32 v140, 16, v94
	v_and_b32_e32 v141, 0xffff0000, v94
	v_pk_fma_f32 v[0:1], v[112:113], v[140:141], v[0:1]
	v_lshlrev_b32_e32 v140, 16, v95
	v_and_b32_e32 v141, 0xffff0000, v95
	v_pk_fma_f32 v[2:3], v[114:115], v[140:141], v[2:3]
	v_lshlrev_b32_e32 v140, 16, v96
	v_and_b32_e32 v141, 0xffff0000, v96
	v_pk_fma_f32 v[12:13], v[116:117], v[140:141], v[12:13]
	v_lshlrev_b32_e32 v140, 16, v97
	v_and_b32_e32 v141, 0xffff0000, v97
	v_pk_fma_f32 v[14:15], v[118:119], v[140:141], v[14:15]
	v_lshlrev_b32_e32 v140, 16, v98
	v_and_b32_e32 v141, 0xffff0000, v98
	v_pk_fma_f32 v[8:9], v[120:121], v[140:141], v[8:9]
	v_lshlrev_b32_e32 v140, 16, v99
	v_and_b32_e32 v141, 0xffff0000, v99
	v_pk_fma_f32 v[10:11], v[122:123], v[140:141], v[10:11]
	v_lshlrev_b32_e32 v140, 16, v100
	v_and_b32_e32 v141, 0xffff0000, v100
	v_pk_fma_f32 v[20:21], v[124:125], v[140:141], v[20:21]
	v_lshlrev_b32_e32 v140, 16, v101
	v_and_b32_e32 v141, 0xffff0000, v101
	v_pk_fma_f32 v[22:23], v[126:127], v[140:141], v[22:23]
	v_lshlrev_b32_e32 v140, 16, v102
	v_and_b32_e32 v141, 0xffff0000, v102
	v_pk_fma_f32 v[16:17], v[128:129], v[140:141], v[16:17]
	v_lshlrev_b32_e32 v140, 16, v103
	v_and_b32_e32 v141, 0xffff0000, v103
	v_pk_fma_f32 v[18:19], v[130:131], v[140:141], v[18:19]
	v_lshlrev_b32_e32 v140, 16, v104
	v_and_b32_e32 v141, 0xffff0000, v104
	v_pk_fma_f32 v[28:29], v[132:133], v[140:141], v[28:29]
	v_lshlrev_b32_e32 v140, 16, v105
	v_and_b32_e32 v141, 0xffff0000, v105
	v_pk_fma_f32 v[30:31], v[134:135], v[140:141], v[30:31]
	v_lshlrev_b32_e32 v140, 16, v106
	v_and_b32_e32 v141, 0xffff0000, v106
	v_pk_fma_f32 v[24:25], v[136:137], v[140:141], v[24:25]
	v_lshlrev_b32_e32 v140, 16, v107
	v_and_b32_e32 v141, 0xffff0000, v107
	v_pk_fma_f32 v[26:27], v[138:139], v[140:141], v[26:27]
	s_branch .Lssdx_tail
.Lssdx_slow:
	s_and_saveexec_b64 s[2:3], s[6:7]
	s_cbranch_execnz .LBB0_1036
	s_or_b64 exec, exec, s[2:3]
	s_and_saveexec_b64 s[2:3], s[8:9]
	s_cbranch_execnz .LBB0_1037

.Lssdx_tail:
	s_waitcnt vmcnt(2)
	v_mul_f32_e32 v32, 0xbfb8aa3b, v20
	v_mul_f32_e32 v33, 0xbfb8aa3b, v21
	v_exp_f32_e32 v32, v32
	v_exp_f32_e32 v33, v33
	v_lshrrev_b32_e32 v67, 5, v38
	v_and_b32_e32 v68, 31, v66
	v_add_f32_e32 v32, 1.0, v32
	v_add_f32_e32 v33, 1.0, v33
	v_rcp_f32_e32 v32, v32
	v_rcp_f32_e32 v33, v33
	v_lshlrev_b32_e32 v70, 3, v67
	v_pk_mul_f32 v[20:21], v[20:21], v[32:33]
	v_mul_f32_e32 v32, 0xbfb8aa3b, v22
	v_mul_f32_e32 v33, 0xbfb8aa3b, v23
	v_exp_f32_e32 v32, v32
	v_exp_f32_e32 v33, v33
	v_add_f32_e32 v32, 1.0, v32
	v_add_f32_e32 v33, 1.0, v33
	v_rcp_f32_e32 v32, v32
	v_rcp_f32_e32 v33, v33
	s_nop 0
	v_pk_mul_f32 v[22:23], v[22:23], v[32:33]
	v_mul_f32_e32 v32, 0xbfb8aa3b, v16
	v_mul_f32_e32 v33, 0xbfb8aa3b, v17
	v_exp_f32_e32 v32, v32
	v_exp_f32_e32 v33, v33
	v_add_f32_e32 v32, 1.0, v32
	v_add_f32_e32 v33, 1.0, v33
	v_rcp_f32_e32 v32, v32
	v_rcp_f32_e32 v33, v33
	s_nop 0
	v_pk_mul_f32 v[16:17], v[16:17], v[32:33]
	v_mul_f32_e32 v32, 0xbfb8aa3b, v18
	v_mul_f32_e32 v33, 0xbfb8aa3b, v19
	v_exp_f32_e32 v32, v32
	v_exp_f32_e32 v33, v33
	v_add_f32_e32 v32, 1.0, v32
	v_add_f32_e32 v33, 1.0, v33
	v_rcp_f32_e32 v32, v32
	v_rcp_f32_e32 v33, v33
	s_nop 0
	v_pk_mul_f32 v[18:19], v[18:19], v[32:33]
	v_mul_f32_e32 v32, 0xbfb8aa3b, v12
	v_mul_f32_e32 v33, 0xbfb8aa3b, v13
	v_exp_f32_e32 v32, v32
	v_exp_f32_e32 v33, v33
	v_add_f32_e32 v32, 1.0, v32
	v_add_f32_e32 v33, 1.0, v33
	v_rcp_f32_e32 v32, v32
	v_rcp_f32_e32 v33, v33
	s_nop 0
	v_pk_mul_f32 v[12:13], v[12:13], v[32:33]
	v_mul_f32_e32 v32, 0xbfb8aa3b, v14
	v_mul_f32_e32 v33, 0xbfb8aa3b, v15
	v_exp_f32_e32 v32, v32
	v_exp_f32_e32 v33, v33
	v_add_f32_e32 v32, 1.0, v32
	v_add_f32_e32 v33, 1.0, v33
	v_rcp_f32_e32 v32, v32
	v_rcp_f32_e32 v33, v33
	s_nop 0
	v_pk_mul_f32 v[14:15], v[14:15], v[32:33]
	v_mul_f32_e32 v32, 0xbfb8aa3b, v8
	v_mul_f32_e32 v33, 0xbfb8aa3b, v9
	v_exp_f32_e32 v32, v32
	v_exp_f32_e32 v33, v33
	v_add_f32_e32 v32, 1.0, v32
	v_add_f32_e32 v33, 1.0, v33
	v_rcp_f32_e32 v32, v32
	v_rcp_f32_e32 v33, v33
	s_nop 0
	v_pk_mul_f32 v[8:9], v[8:9], v[32:33]
	v_mul_f32_e32 v32, 0xbfb8aa3b, v10
	v_mul_f32_e32 v33, 0xbfb8aa3b, v11
	v_exp_f32_e32 v32, v32
	v_exp_f32_e32 v33, v33
	v_add_f32_e32 v32, 1.0, v32
	v_add_f32_e32 v33, 1.0, v33
	v_rcp_f32_e32 v32, v32
	v_rcp_f32_e32 v33, v33
	s_nop 0
	v_pk_mul_f32 v[10:11], v[10:11], v[32:33]
	v_mul_f32_e32 v32, 0xbfb8aa3b, v4
	v_mul_f32_e32 v33, 0xbfb8aa3b, v5
	v_exp_f32_e32 v32, v32
	v_exp_f32_e32 v33, v33
	v_add_f32_e32 v32, 1.0, v32
	v_add_f32_e32 v33, 1.0, v33
	v_rcp_f32_e32 v32, v32
	v_rcp_f32_e32 v33, v33
	s_nop 0
	v_pk_mul_f32 v[4:5], v[4:5], v[32:33]
	v_mul_f32_e32 v32, 0xbfb8aa3b, v6
	v_mul_f32_e32 v33, 0xbfb8aa3b, v7
	v_exp_f32_e32 v32, v32
	v_exp_f32_e32 v33, v33
	v_add_f32_e32 v32, 1.0, v32
	v_add_f32_e32 v33, 1.0, v33
	v_rcp_f32_e32 v32, v32
	v_rcp_f32_e32 v33, v33
	s_nop 0
	v_pk_mul_f32 v[6:7], v[6:7], v[32:33]
	v_mul_f32_e32 v32, 0xbfb8aa3b, v0
	v_mul_f32_e32 v33, 0xbfb8aa3b, v1
	v_exp_f32_e32 v32, v32
	v_exp_f32_e32 v33, v33
	v_add_f32_e32 v32, 1.0, v32
	v_add_f32_e32 v33, 1.0, v33
	v_rcp_f32_e32 v32, v32
	v_rcp_f32_e32 v33, v33
	s_nop 0
	v_pk_mul_f32 v[34:35], v[0:1], v[32:33]
	v_mul_f32_e32 v0, 0xbfb8aa3b, v2
	v_mul_f32_e32 v1, 0xbfb8aa3b, v3
	v_exp_f32_e32 v0, v0
	v_exp_f32_e32 v1, v1
	v_ashrrev_i32_e32 v32, 6, v66
	v_lshl_or_b32 v69, v32, 5, v68
	v_add_f32_e32 v0, 1.0, v0
	v_add_f32_e32 v1, 1.0, v1
	v_rcp_f32_e32 v0, v0
	v_rcp_f32_e32 v1, v1
	v_add_u32_e32 v64, s86, v69
	v_pk_mul_f32 v[40:41], v[2:3], v[0:1]
	s_waitcnt vmcnt(0)
	v_mul_f32_e32 v0, 0xbfb8aa3b, v28
	v_exp_f32_e32 v0, v0
	s_nop 0
	v_add_f32_e32 v0, 1.0, v0
	v_rcp_f32_e32 v42, v0
	v_mul_f32_e32 v0, 0xbfb8aa3b, v29
	v_exp_f32_e32 v0, v0
	s_nop 0
	v_add_f32_e32 v0, 1.0, v0
	v_rcp_f32_e32 v43, v0
	v_mul_f32_e32 v0, 0xbfb8aa3b, v30
	v_exp_f32_e32 v0, v0
	s_nop 0
	v_add_f32_e32 v0, 1.0, v0
	v_rcp_f32_e32 v44, v0
	v_mul_f32_e32 v0, 0xbfb8aa3b, v31
	v_exp_f32_e32 v0, v0
	s_nop 0
	v_add_f32_e32 v0, 1.0, v0
	v_rcp_f32_e32 v45, v0
	v_mul_f32_e32 v0, 0xbfb8aa3b, v24
	v_exp_f32_e32 v0, v0
	s_nop 0
	v_add_f32_e32 v0, 1.0, v0
	v_rcp_f32_e32 v46, v0
	v_mul_f32_e32 v0, 0xbfb8aa3b, v25
	v_exp_f32_e32 v0, v0
	s_nop 0
	v_add_f32_e32 v0, 1.0, v0
	v_rcp_f32_e32 v47, v0
	v_mul_f32_e32 v0, 0xbfb8aa3b, v26
	v_exp_f32_e32 v0, v0
	s_nop 0
	v_add_f32_e32 v0, 1.0, v0
	v_rcp_f32_e32 v48, v0
	v_mul_f32_e32 v0, 0xbfb8aa3b, v27
	v_exp_f32_e32 v0, v0
	s_nop 0
	v_add_f32_e32 v0, 1.0, v0
	v_rcp_f32_e32 v49, v0
	v_lshl_add_u32 v0, v39, 2, s89
	ds_read_b32 v38, v0 offset:33280
	s_waitcnt lgkmcnt(0)
	v_pk_mul_f32 v[0:1], v[4:5], v[38:39] op_sel_hi:[1,0]
	v_pk_mul_f32 v[2:3], v[6:7], v[38:39] op_sel_hi:[1,0]
	v_cvt_pk_bf16_f32 v0, v0, v1
	v_cvt_pk_bf16_f32 v1, v2, v3
	v_pk_mul_f32 v[2:3], v[34:35], v[38:39] op_sel_hi:[1,0]
	v_pk_mul_f32 v[4:5], v[40:41], v[38:39] op_sel_hi:[1,0]
	v_cvt_pk_bf16_f32 v2, v2, v3
	v_cvt_pk_bf16_f32 v3, v4, v5
	ds_write_b128 v36, v[0:3] offset:16384
	v_pk_mul_f32 v[0:1], v[12:13], v[38:39] op_sel_hi:[1,0]
	v_pk_mul_f32 v[2:3], v[14:15], v[38:39] op_sel_hi:[1,0]
	v_cvt_pk_bf16_f32 v0, v0, v1
	v_cvt_pk_bf16_f32 v1, v2, v3
	v_pk_mul_f32 v[2:3], v[8:9], v[38:39] op_sel_hi:[1,0]
	v_pk_mul_f32 v[4:5], v[10:11], v[38:39] op_sel_hi:[1,0]
	v_cvt_pk_bf16_f32 v2, v2, v3
	v_cvt_pk_bf16_f32 v3, v4, v5
	ds_write_b128 v36, v[0:3] offset:16400
	v_pk_mul_f32 v[0:1], v[20:21], v[38:39] op_sel_hi:[1,0]
	v_pk_mul_f32 v[2:3], v[22:23], v[38:39] op_sel_hi:[1,0]
	v_cvt_pk_bf16_f32 v0, v0, v1
	v_cvt_pk_bf16_f32 v1, v2, v3
	v_pk_mul_f32 v[2:3], v[16:17], v[38:39] op_sel_hi:[1,0]
	v_pk_mul_f32 v[4:5], v[18:19], v[38:39] op_sel_hi:[1,0]
	v_cvt_pk_bf16_f32 v2, v2, v3
	v_cvt_pk_bf16_f32 v3, v4, v5
	ds_write_b128 v36, v[0:3] offset:16416
	v_pk_mul_f32 v[0:1], v[28:29], v[42:43]
	v_pk_mul_f32 v[2:3], v[30:31], v[44:45]
	v_pk_mul_f32 v[0:1], v[38:39], v[0:1] op_sel_hi:[0,1]
	v_pk_mul_f32 v[2:3], v[38:39], v[2:3] op_sel_hi:[0,1]
	v_cvt_pk_bf16_f32 v0, v0, v1
	v_cvt_pk_bf16_f32 v1, v2, v3
	v_pk_mul_f32 v[2:3], v[24:25], v[46:47]
	v_pk_mul_f32 v[4:5], v[26:27], v[48:49]
	v_pk_mul_f32 v[2:3], v[38:39], v[2:3] op_sel_hi:[0,1]
	v_pk_mul_f32 v[4:5], v[38:39], v[4:5] op_sel_hi:[0,1]
	v_cvt_pk_bf16_f32 v2, v2, v3
	v_cvt_pk_bf16_f32 v3, v4, v5
	v_or_b32_e32 v12, s5, v70
	ds_write_b128 v36, v[0:3] offset:16432
	v_add_u32_e32 v0, -3, v64
	v_lshlrev_b32_e32 v168, 2, v12
	v_mad_i64_i32 v[10:11], s[0:1], v0, s93, 0
	global_load_dwordx4 v[0:3], v168, s[74:75] offset:1552
	global_load_dwordx4 v[4:7], v168, s[74:75] offset:1536
	v_lshlrev_b32_e32 v12, 1, v12
	v_mov_b32_e32 v13, v169
	v_add_u32_e32 v20, s68, v69
	v_lshl_add_u64 v[16:17], s[30:31], 0, v[12:13]
	v_cmp_lt_i32_e64 s[6:7], 2, v20
	v_lshl_add_u64 v[8:9], s[14:15], 0, v[168:169]
	v_lshl_add_u64 v[10:11], v[16:17], 0, v[10:11]
	s_and_saveexec_b64 s[2:3], s[6:7]
	s_cbranch_execz .LBB0_980
	global_load_dwordx4 v[12:15], v[10:11], off offset:2304
	global_load_dwordx4 v[22:25], v[8:9], off offset:1552
	global_load_dwordx4 v[26:29], v[8:9], off offset:1536
	s_waitcnt vmcnt(2)
	v_lshlrev_b32_e32 v18, 16, v12
	v_and_b32_e32 v19, 0xffff0000, v12
	v_lshlrev_b32_e32 v12, 16, v13
	v_and_b32_e32 v13, 0xffff0000, v13
	s_waitcnt vmcnt(0)
	v_pk_fma_f32 v[6:7], v[28:29], v[12:13], v[6:7]
	v_lshlrev_b32_e32 v12, 16, v14
	v_and_b32_e32 v13, 0xffff0000, v14
	v_pk_fma_f32 v[0:1], v[22:23], v[12:13], v[0:1]
	v_lshlrev_b32_e32 v12, 16, v15
	v_and_b32_e32 v13, 0xffff0000, v15
	v_pk_fma_f32 v[4:5], v[26:27], v[18:19], v[4:5]
	v_pk_fma_f32 v[2:3], v[24:25], v[12:13], v[2:3]
